# attention: K/V tile DMA issued after a mid-interval barrier, 1.4 intervals ahead, counted vmcnt(6) at tile barriers
# speedup vs baseline: 1.0123x; 1.0024x over previous
.LBB0_474:
	s_cmp_eq_u32 s66, 1
	s_mov_b32 s4, 0x10576243
	s_cselect_b32 s4, s4, 0x34102657
	s_cmp_lg_u32 s66, 0
	s_cselect_b32 s4, s4, 0x76543210
	s_lshr_b32 s4, s4, s64
	s_and_b32 s69, s4, 7
	s_add_i32 s4, s66, s65
	s_ashr_i32 s70, s4, 1
	s_and_b32 s67, s4, 1
	s_mul_hi_i32 s4, s70, 0x2aaaaaab
	s_lshr_b32 s5, s4, 31
	s_ashr_i32 s4, s4, 1
	s_add_i32 s4, s4, s5
	s_mul_i32 s5, s4, 12
	s_sub_i32 s5, s70, s5
	s_mul_i32 s4, s4, 24
	s_lshl_b32 s5, s5, 1
	s_add_i32 s68, s4, s5
	s_or_b32 s4, s68, s67
	s_ashr_i32 s5, s4, 31
	s_lshl_b64 s[36:37], s[4:5], 19
	s_add_u32 s76, s6, s36
	s_addc_u32 s77, s7, s37
	s_addk_i32 s4, 0x60
	s_ashr_i32 s5, s4, 31
	s_lshl_b64 s[4:5], s[4:5], 19
	s_add_u32 s40, s6, s4
	v_mov_b32_e32 v11, v208
	s_addc_u32 s41, s7, s5
	s_add_i32 s4, s68, 0xc0
	s_ashr_i32 s5, s4, 31
	v_ashrrev_i32_e32 v9, 4, v11
	v_add_u32_e32 v1, s24, v9
	s_lshl_b64 s[4:5], s[4:5], 19
	v_lshlrev_b32_e32 v2, 8, v1
	v_lshlrev_b32_e32 v0, 1, v1
	v_bfe_u32 v3, v1, 3, 1
	v_add_u32_e32 v1, 4, v1
	s_add_u32 s38, s6, s4
	v_xor_b32_e32 v1, v1, v11
	s_addc_u32 s39, s7, s5
	s_add_i32 s36, s68, 0xc1
	v_lshlrev_b32_e32 v1, 4, v1
	s_ashr_i32 s37, s36, 31
	v_and_b32_e32 v12, 15, v11
	v_and_b32_e32 v0, 14, v0
	v_and_b32_e32 v10, 0xf0, v1
	s_mov_b32 m0, s30
	s_lshl_b64 s[36:37], s[36:37], 19
	v_bitop3_b32 v0, v0, v12, v3 bitop3:0x36
	v_or_b32_e32 v6, v10, v2
	v_add_u32_e32 v1, 0x2000, v2
	s_add_u32 s36, s6, s36
	v_lshlrev_b32_e32 v8, 4, v0
	v_or_b32_e32 v4, v10, v1
	global_load_lds_dwordx4 v6, s[40:41]
	s_mov_b32 m0, s35
	s_addc_u32 s37, s7, s37
	s_lshl_b32 s71, s69, 8
	v_or_b32_e32 v0, v8, v2
	global_load_lds_dwordx4 v4, s[40:41]
	s_mov_b32 m0, s42
	s_add_i32 s68, s71, s25
	v_or_b32_e32 v2, v8, v1
	global_load_lds_dwordx4 v0, s[38:39]
	s_mov_b32 m0, s43
	v_lshlrev_b32_e32 v14, 3, v9
	global_load_lds_dwordx4 v2, s[38:39]
	s_mov_b32 m0, s52
	v_or_b32_e32 v192, s68, v12
	v_ashrrev_i32_e32 v15, 31, v14
	global_load_lds_dwordx4 v0, s[36:37]
	s_mov_b32 m0, s53
	v_lshl_add_u64 v[14:15], v[14:15], 1, s[76:77]
	v_lshlrev_b64 v[16:17], 8, v[192:193]
	global_load_lds_dwordx4 v2, s[36:37]
	v_lshl_add_u64 v[16:17], v[14:15], 0, v[16:17]
	v_or_b32_e32 v194, 16, v192
	v_mov_b32_e32 v195, v193
	global_load_dwordx4 v[36:39], v[16:17], off
	global_load_dwordx4 v[44:47], v[16:17], off offset:64
	global_load_dwordx4 v[48:51], v[16:17], off offset:128
	global_load_dwordx4 v[52:55], v[16:17], off offset:192
	v_lshlrev_b64 v[16:17], 8, v[194:195]
	v_lshl_add_u64 v[14:15], v[14:15], 0, v[16:17]
	global_load_dwordx4 v[56:59], v[14:15], off
	global_load_dwordx4 v[60:63], v[14:15], off offset:64
	global_load_dwordx4 v[64:67], v[14:15], off offset:128
	global_load_dwordx4 v[68:71], v[14:15], off offset:192
	s_add_u32 s40, s40, 0x4000
	v_mov_b32_e32 v7, v193
	s_addc_u32 s41, s41, 0
	s_mov_b32 m0, s54
	v_mov_b32_e32 v5, v193
	v_lshl_add_u64 v[6:7], s[40:41], 0, v[6:7]
	s_add_u32 s38, s38, 0x4000
	v_mov_b32_e32 v1, v193
	global_load_lds_dwordx4 v[6:7], off
	v_lshl_add_u64 v[4:5], s[40:41], 0, v[4:5]
	s_mov_b32 m0, s55
	s_addc_u32 s39, s39, 0
	v_mov_b32_e32 v3, v193
	global_load_lds_dwordx4 v[4:5], off
	v_lshl_add_u64 v[4:5], s[38:39], 0, v[0:1]
	s_mov_b32 m0, s56
	s_add_u32 s36, s36, 0x4000
	global_load_lds_dwordx4 v[4:5], off
	v_lshl_add_u64 v[4:5], s[38:39], 0, v[2:3]
	s_mov_b32 m0, s57
	s_addc_u32 s37, s37, 0
	global_load_lds_dwordx4 v[4:5], off
	v_lshl_add_u64 v[0:1], s[36:37], 0, v[0:1]
	s_mov_b32 m0, s58
	s_nop 0
	global_load_lds_dwordx4 v[0:1], off
	v_lshl_add_u64 v[0:1], s[36:37], 0, v[2:3]
	s_mov_b32 m0, s59
	s_nop 0
	global_load_lds_dwordx4 v[0:1], off
	s_and_b64 vcc, exec, s[0:1]
	s_cbranch_vccnz .LBB0_476
	s_waitcnt vmcnt(6)
	s_barrier
.LBB0_476:
	v_lshlrev_b32_e32 v198, 2, v9
	v_lshrrev_b32_e32 v3, 2, v12
	v_bitop3_b32 v2, v9, v11, 3 bitop3:0x78
	v_or_b32_e32 v3, v198, v3
	v_lshlrev_b32_e32 v1, 8, v12
	v_lshlrev_b32_e32 v2, 4, v2
	v_lshlrev_b32_e32 v4, 1, v3
	v_ashrrev_i32_e32 v5, 5, v11
	v_and_or_b32 v4, v4, 14, v5
	v_add3_u32 v199, 0, v1, v2
	v_lshl_add_u32 v1, v11, 4, 64
	v_and_b32_e32 v214, 0xc0, v1
	v_bitop3_b32 v215, v1, 64, v210 bitop3:0x6c
	v_bitop3_b32 v216, v1, s60, v210 bitop3:0x6c
	v_bitop3_b32 v217, v1, s33, v1 bitop3:0xc
	v_lshlrev_b32_e32 v1, 4, v4
	s_movk_i32 s36, 0x60
	v_bitop3_b32 v221, v1, s36, v211 bitop3:0x6c
	s_movk_i32 s36, 0xa0
	v_cndmask_b32_e64 v0, 0, 1, s[26:27]
	v_bitop3_b32 v223, v1, s36, v211 bitop3:0x6c
	s_movk_i32 s36, 0xe0
	s_lshl_b32 s40, s70, 1
	v_bitop3_b32 v225, v1, s36, v211 bitop3:0x6c
	v_readfirstlane_b32 s36, v0
	v_lshrrev_b32_e32 v6, 1, v11
	s_or_b32 s36, s40, s36
	v_xor_b32_e32 v5, v6, v5
	s_addk_i32 s36, 0x60
	s_lshl_b32 s69, s69, 2
	v_lshlrev_b32_e32 v5, 4, v5
	v_lshlrev_b32_e32 v6, 3, v11
	s_ashr_i32 s37, s36, 31
	s_add_i32 s69, s69, 4
	v_lshlrev_b32_e32 v3, 8, v3
	v_and_b32_e32 v5, 16, v5
	v_and_b32_e32 v6, 8, v6
	s_or_b32 s70, s68, 31
	s_lshl_b64 s[36:37], s[36:37], 19
	v_lshlrev_b32_e32 v2, 8, v9
	v_or3_b32 v213, v6, v5, v3
	v_add_u32_e32 v3, s29, v2
	s_add_u32 s36, s74, s36
	v_and_b32_e32 v218, 0xffffffe0, v1
	v_bitop3_b32 v219, v1, 32, v211 bitop3:0x6c
	v_bitop3_b32 v220, v1, 64, v211 bitop3:0x6c
	v_bitop3_b32 v222, v1, s60, v211 bitop3:0x6c
	v_bitop3_b32 v224, v1, s33, v211 bitop3:0x6c
	v_add_u32_e32 v0, v3, v10
	v_mov_b32_e32 v1, v193
	s_addc_u32 s37, s75, s37
	v_add_u32_e32 v2, s31, v2
	v_lshl_add_u64 v[200:201], s[36:37], 0, v[0:1]
	v_add_u32_e32 v0, v2, v10
	s_add_u32 s4, s74, s4
	v_lshl_add_u64 v[202:203], s[36:37], 0, v[0:1]
	v_add_u32_e32 v0, v3, v8
	s_addc_u32 s5, s75, s5
	v_lshl_add_u64 v[204:205], s[4:5], 0, v[0:1]
	v_add_u32_e32 v0, v2, v8
	v_mov_b32_e32 v2, v193
	v_mov_b32_e32 v3, v193
	v_lshl_add_u64 v[206:207], s[4:5], 0, v[0:1]
	v_mov_b32_e32 v0, v193
	v_mov_b64_e32 v[10:11], v[2:3]
	v_mov_b64_e32 v[18:19], v[2:3]
	v_mov_b64_e32 v[22:23], v[2:3]
	v_mov_b64_e32 v[26:27], v[2:3]
	v_mov_b64_e32 v[30:31], v[2:3]
	v_mov_b64_e32 v[34:35], v[2:3]
	v_mov_b64_e32 v[42:43], v[2:3]
	v_mov_b64_e32 v[74:75], v[2:3]
	v_mov_b64_e32 v[78:79], v[2:3]
	v_mov_b64_e32 v[82:83], v[2:3]
	v_mov_b64_e32 v[86:87], v[2:3]
	v_mov_b64_e32 v[90:91], v[2:3]
	v_mov_b64_e32 v[94:95], v[2:3]
	v_mov_b64_e32 v[98:99], v[2:3]
	v_mov_b64_e32 v[102:103], v[2:3]
	v_mov_b64_e32 v[106:107], v[2:3]
	v_mov_b64_e32 v[110:111], v[2:3]
	v_mov_b64_e32 v[114:115], v[2:3]
	v_mov_b64_e32 v[118:119], v[2:3]
	v_mov_b64_e32 v[122:123], v[2:3]
	v_mov_b64_e32 v[126:127], v[2:3]
	v_mov_b64_e32 v[130:131], v[2:3]
	v_mov_b64_e32 v[134:135], v[2:3]
	v_mov_b64_e32 v[138:139], v[2:3]
	v_mov_b64_e32 v[142:143], v[2:3]
	v_mov_b64_e32 v[146:147], v[2:3]
	v_mov_b64_e32 v[150:151], v[2:3]
	v_mov_b64_e32 v[154:155], v[2:3]
	v_mov_b64_e32 v[158:159], v[2:3]
	v_mov_b64_e32 v[14:15], v[2:3]
	v_mov_b64_e32 v[6:7], v[2:3]
	s_mov_b32 s41, 2
	v_add_u32_e32 v226, -16, v192
	s_addk_i32 s71, 0x100
	v_mov_b32_e32 v196, v193
	v_mov_b32_e32 v197, v193
	v_mov_b32_e32 v227, 0xf149f2ca
	s_mov_b64 s[36:37], 0
	s_mov_b32 s73, 0
	v_mov_b64_e32 v[8:9], v[0:1]
	v_mov_b64_e32 v[16:17], v[0:1]
	v_mov_b64_e32 v[20:21], v[0:1]
	v_mov_b64_e32 v[24:25], v[0:1]
	v_mov_b64_e32 v[28:29], v[0:1]
	v_mov_b64_e32 v[32:33], v[0:1]
	v_mov_b64_e32 v[40:41], v[0:1]
	v_mov_b64_e32 v[72:73], v[0:1]
	v_mov_b64_e32 v[76:77], v[0:1]
	v_mov_b64_e32 v[80:81], v[0:1]
	v_mov_b64_e32 v[84:85], v[0:1]
	v_mov_b64_e32 v[88:89], v[0:1]
	v_mov_b64_e32 v[92:93], v[0:1]
	v_mov_b64_e32 v[96:97], v[0:1]
	v_mov_b64_e32 v[100:101], v[0:1]
	v_mov_b64_e32 v[104:105], v[0:1]
	v_mov_b64_e32 v[108:109], v[0:1]
	v_mov_b64_e32 v[112:113], v[0:1]
	v_mov_b64_e32 v[116:117], v[0:1]
	v_mov_b64_e32 v[120:121], v[0:1]
	v_mov_b64_e32 v[124:125], v[0:1]
	v_mov_b64_e32 v[128:129], v[0:1]
	v_mov_b64_e32 v[132:133], v[0:1]
	v_mov_b64_e32 v[136:137], v[0:1]
	v_mov_b64_e32 v[140:141], v[0:1]
	v_mov_b64_e32 v[144:145], v[0:1]
	v_mov_b64_e32 v[148:149], v[0:1]
	v_mov_b64_e32 v[152:153], v[0:1]
	v_mov_b64_e32 v[156:157], v[0:1]
	v_mov_b32_e32 v228, 0xf149f2ca
	v_mov_b64_e32 v[12:13], v[0:1]
	v_mov_b64_e32 v[4:5], v[0:1]
	s_mov_b32 s77, 0
	s_waitcnt vmcnt(6)
.LBB0_477:
	s_add_i32 s4, s77, 1
	s_cmp_lg_u32 s77, 2
	s_cselect_b32 s76, s4, 0
	s_andn2_b64 vcc, exec, s[10:11]
	s_cbranch_vccnz .LBB0_480
	s_add_i32 s4, s41, -1
	s_cmp_lt_u32 s4, s69
	s_cbranch_scc1 .Lx_w6_a
	s_waitcnt vmcnt(0)
	s_branch .Lx_wd_a
.Lx_w6_a:
	s_waitcnt vmcnt(6)
.Lx_wd_a:
	s_barrier
.LBB0_480:
	s_cmp_le_u32 s73, s70
	s_cselect_b64 s[38:39], -1, 0
	s_cmp_gt_u32 s73, s70
	s_cbranch_scc1 .Lx_inact
	s_and_b32 s4, s36, 0x4000
	v_add_u32_e32 v229, s4, v199
	v_add_u32_e32 v246, v229, v214
	v_add_u32_e32 v247, v229, v215
	v_add_u32_e32 v248, v229, v216
	v_add_u32_e32 v249, v229, v217
	s_add_i32 s4, s73, 63
	s_cmp_le_u32 s4, s68
	ds_read_b128 v[230:233], v246
	ds_read_b128 v[234:237], v247
	ds_read_b128 v[238:241], v248
	ds_read_b128 v[242:245], v249
	ds_read_b128 v[184:187], v246 offset:4096
	ds_read_b128 v[188:191], v247 offset:4096
	s_waitcnt lgkmcnt(5)
	v_mfma_f32_16x16x32_bf16 v[164:167], v[230:233], v[36:39], 0
	v_mfma_f32_16x16x32_bf16 v[160:163], v[230:233], v[56:59], 0
	ds_read_b128 v[230:233], v248 offset:4096
	s_waitcnt lgkmcnt(5)
	v_mfma_f32_16x16x32_bf16 v[164:167], v[234:237], v[44:47], v[164:167]
	v_mfma_f32_16x16x32_bf16 v[160:163], v[234:237], v[60:63], v[160:163]
	ds_read_b128 v[234:237], v249 offset:4096
	s_waitcnt lgkmcnt(5)
	v_mfma_f32_16x16x32_bf16 v[164:167], v[238:241], v[48:51], v[164:167]
	v_mfma_f32_16x16x32_bf16 v[160:163], v[238:241], v[64:67], v[160:163]
	ds_read_b128 v[238:241], v246 offset:8192
	s_waitcnt lgkmcnt(5)
	v_mfma_f32_16x16x32_bf16 v[164:167], v[242:245], v[52:55], v[164:167]
	v_mfma_f32_16x16x32_bf16 v[160:163], v[242:245], v[68:71], v[160:163]
	ds_read_b128 v[242:245], v247 offset:8192
	s_waitcnt lgkmcnt(5)
	v_mfma_f32_16x16x32_bf16 v[180:183], v[184:187], v[36:39], 0
	v_mfma_f32_16x16x32_bf16 v[172:175], v[184:187], v[56:59], 0
	ds_read_b128 v[184:187], v248 offset:8192
	s_waitcnt lgkmcnt(5)
	v_mfma_f32_16x16x32_bf16 v[180:183], v[188:191], v[44:47], v[180:183]
	v_mfma_f32_16x16x32_bf16 v[172:175], v[188:191], v[60:63], v[172:175]
	ds_read_b128 v[188:191], v249 offset:8192
	s_waitcnt lgkmcnt(5)
	v_mfma_f32_16x16x32_bf16 v[180:183], v[230:233], v[48:51], v[180:183]
	v_mfma_f32_16x16x32_bf16 v[172:175], v[230:233], v[64:67], v[172:175]
	ds_read_b128 v[230:233], v246 offset:12288
	s_waitcnt lgkmcnt(5)
	v_mfma_f32_16x16x32_bf16 v[180:183], v[234:237], v[52:55], v[180:183]
	v_mfma_f32_16x16x32_bf16 v[172:175], v[234:237], v[68:71], v[172:175]
	ds_read_b128 v[234:237], v247 offset:12288
	s_waitcnt lgkmcnt(5)
	v_mfma_f32_16x16x32_bf16 v[176:179], v[238:241], v[36:39], 0
	v_mfma_f32_16x16x32_bf16 v[168:171], v[238:241], v[56:59], 0
	ds_read_b128 v[238:241], v248 offset:12288
	s_waitcnt lgkmcnt(5)
	v_mfma_f32_16x16x32_bf16 v[176:179], v[242:245], v[44:47], v[176:179]
	v_mfma_f32_16x16x32_bf16 v[168:171], v[242:245], v[60:63], v[168:171]
	ds_read_b128 v[242:245], v249 offset:12288
	s_waitcnt lgkmcnt(5)
	v_mfma_f32_16x16x32_bf16 v[176:179], v[184:187], v[48:51], v[176:179]
	v_mfma_f32_16x16x32_bf16 v[168:171], v[184:187], v[64:67], v[168:171]
	s_waitcnt lgkmcnt(4)
	v_mfma_f32_16x16x32_bf16 v[176:179], v[188:191], v[52:55], v[176:179]
	v_mfma_f32_16x16x32_bf16 v[168:171], v[188:191], v[68:71], v[168:171]
	s_waitcnt lgkmcnt(3)
	v_mfma_f32_16x16x32_bf16 v[188:191], v[230:233], v[36:39], 0
	v_mfma_f32_16x16x32_bf16 v[184:187], v[230:233], v[56:59], 0
	s_waitcnt lgkmcnt(2)
	v_mfma_f32_16x16x32_bf16 v[188:191], v[234:237], v[44:47], v[188:191]
	v_mfma_f32_16x16x32_bf16 v[184:187], v[234:237], v[60:63], v[184:187]
	s_waitcnt lgkmcnt(1)
	v_mfma_f32_16x16x32_bf16 v[188:191], v[238:241], v[48:51], v[188:191]
	v_mfma_f32_16x16x32_bf16 v[184:187], v[238:241], v[64:67], v[184:187]
	s_waitcnt lgkmcnt(0)
	v_mfma_f32_16x16x32_bf16 v[188:191], v[242:245], v[52:55], v[188:191]
	v_mfma_f32_16x16x32_bf16 v[184:187], v[242:245], v[68:71], v[184:187]
	s_and_b64 vcc, exec, s[0:1]
	s_cbranch_vccnz .Lx_qk_done
	s_barrier
	s_cmp_ge_u32 s41, s69
	s_cbranch_scc1 .Lx_nodma_l
	s_lshl_b32 s4, s76, 15
	s_add_i32 s4, s4, 0x8000
	s_cmp_lg_u32 s76, 2
	s_cselect_b32 s4, s4, 0
	s_and_b32 s5, s36, 0x4000
	s_add_i32 s5, s30, s5
	v_lshl_add_u64 v[236:237], v[200:201], 0, s[36:37]
	v_lshl_add_u64 v[236:237], v[236:237], 0, s[20:21]
	s_mov_b32 m0, s5
	s_add_i32 s4, s30, s4
	global_load_lds_dwordx4 v[236:237], off
	v_lshl_add_u64 v[236:237], v[202:203], 0, s[36:37]
	v_lshl_add_u64 v[236:237], v[236:237], 0, s[20:21]
	s_add_i32 m0, s5, 0x2000
	s_nop 0
	global_load_lds_dwordx4 v[236:237], off
	v_lshl_add_u64 v[236:237], v[204:205], 0, s[36:37]
	v_lshl_add_u64 v[238:239], v[236:237], 0, s[20:21]
	s_add_i32 m0, s4, 0x8000
	v_lshl_add_u64 v[236:237], v[236:237], 0, s[22:23]
	global_load_lds_dwordx4 v[238:239], off
	v_lshl_add_u64 v[238:239], v[206:207], 0, s[36:37]
	v_lshl_add_u64 v[240:241], v[238:239], 0, s[20:21]
	s_add_i32 m0, s4, 0xa000
	s_nop 0
	global_load_lds_dwordx4 v[240:241], off
	s_add_i32 m0, s4, 0xc000
	s_nop 0
	global_load_lds_dwordx4 v[236:237], off
	s_add_i32 m0, s4, 0xe000
	v_lshl_add_u64 v[236:237], v[238:239], 0, s[22:23]
	global_load_lds_dwordx4 v[236:237], off
.Lx_nodma_l:
.Lx_qk_done:
	s_add_i32 s4, s73, 63
	s_cmp_le_u32 s4, s68
	s_cbranch_scc1 .LBB0_483
	v_add_u32_e32 v229, s73, v198
	v_mov_b32_e32 v230, s61
	v_cmp_gt_i32_e32 vcc, v229, v192
	v_cmp_lt_i32_e64 s[4:5], v229, v192
	v_add_u32_e32 v231, 2, v229
	v_cndmask_b32_e32 v230, v164, v230, vcc
	v_cndmask_b32_e64 v164, v230, v164, s[4:5]
	v_cndmask_b32_e64 v165, v212, v165, s[4:5]
	v_cmp_le_i32_e64 s[4:5], v231, v192
	v_add_u32_e32 v232, 3, v229
	v_mov_b32_e32 v230, s61
	v_cndmask_b32_e64 v166, v212, v166, s[4:5]
	v_cmp_le_i32_e64 s[4:5], v232, v192
	v_add_u32_e32 v233, 17, v229
	v_add_u32_e32 v234, 18, v229
	v_cndmask_b32_e64 v167, v212, v167, s[4:5]
	v_cmp_gt_i32_e64 s[4:5], v229, v226
	v_add_u32_e32 v235, 19, v229
	v_add_u32_e32 v236, 32, v229
	v_cndmask_b32_e64 v180, v180, v230, s[4:5]
	v_cmp_le_i32_e64 s[4:5], v233, v192
	v_add_u32_e32 v237, 33, v229
	v_add_u32_e32 v238, 34, v229
	v_cndmask_b32_e64 v181, v212, v181, s[4:5]
	v_cmp_le_i32_e64 s[4:5], v234, v192
	v_add_u32_e32 v239, 35, v229
	v_add_u32_e32 v240, 48, v229
	v_cndmask_b32_e64 v182, v212, v182, s[4:5]
	v_cmp_le_i32_e64 s[4:5], v235, v192
	v_add_u32_e32 v241, 49, v229
	v_add_u32_e32 v242, 50, v229
	v_cndmask_b32_e64 v183, v212, v183, s[4:5]
	v_cmp_gt_i32_e64 s[4:5], v236, v192
	v_add_u32_e32 v243, 51, v229
	s_nop 0
	v_cndmask_b32_e64 v176, v176, v230, s[4:5]
	v_cmp_le_i32_e64 s[4:5], v237, v192
	s_nop 1
	v_cndmask_b32_e64 v177, v212, v177, s[4:5]
	v_cmp_le_i32_e64 s[4:5], v238, v192
	s_nop 1
	v_cndmask_b32_e64 v178, v212, v178, s[4:5]
	v_cmp_le_i32_e64 s[4:5], v239, v192
	s_nop 1
	v_cndmask_b32_e64 v179, v212, v179, s[4:5]
	v_cmp_gt_i32_e64 s[4:5], v240, v192
	s_nop 1
	v_cndmask_b32_e64 v188, v188, v230, s[4:5]
	v_cmp_le_i32_e64 s[4:5], v241, v192
	s_nop 1
	v_cndmask_b32_e64 v189, v212, v189, s[4:5]
	v_cmp_le_i32_e64 s[4:5], v242, v192
	s_nop 1
	v_cndmask_b32_e64 v190, v212, v190, s[4:5]
	v_cmp_le_i32_e64 s[4:5], v243, v192
	s_nop 1
	v_cndmask_b32_e64 v191, v212, v191, s[4:5]
	v_cmp_gt_i32_e64 s[4:5], v229, v194
	s_nop 1
	v_cndmask_b32_e64 v230, v160, v230, s[4:5]
	v_cmp_lt_i32_e64 s[4:5], v229, v194
	s_nop 1
	v_cndmask_b32_e64 v160, v230, v160, s[4:5]
	v_mov_b32_e32 v230, s61
	v_cndmask_b32_e32 v172, v172, v230, vcc
	v_cmp_le_i32_e32 vcc, v233, v194
	v_cndmask_b32_e64 v161, v212, v161, s[4:5]
	v_cmp_le_i32_e64 s[4:5], v231, v194
	v_cndmask_b32_e32 v173, v212, v173, vcc
	v_cmp_le_i32_e32 vcc, v234, v194
	v_cndmask_b32_e64 v162, v212, v162, s[4:5]
	v_cmp_le_i32_e64 s[4:5], v232, v194
	v_cndmask_b32_e32 v174, v212, v174, vcc
	v_cmp_le_i32_e32 vcc, v235, v194
	v_cndmask_b32_e64 v163, v212, v163, s[4:5]
	s_nop 0
	v_cndmask_b32_e32 v175, v212, v175, vcc
	v_cmp_gt_i32_e32 vcc, v236, v194
	s_nop 1
	v_cndmask_b32_e32 v168, v168, v230, vcc
	v_cmp_le_i32_e32 vcc, v237, v194
	s_nop 1
	v_cndmask_b32_e32 v169, v212, v169, vcc
	v_cmp_le_i32_e32 vcc, v238, v194
	s_nop 1
	v_cndmask_b32_e32 v170, v212, v170, vcc
	v_cmp_le_i32_e32 vcc, v239, v194
	s_nop 1
	v_cndmask_b32_e32 v171, v212, v171, vcc
	v_cmp_gt_i32_e32 vcc, v240, v194
	s_nop 1
	v_cndmask_b32_e32 v184, v184, v230, vcc
	v_cmp_le_i32_e32 vcc, v241, v194
	s_nop 1
	v_cndmask_b32_e32 v185, v212, v185, vcc
	v_cmp_le_i32_e32 vcc, v242, v194
	s_nop 1
	v_cndmask_b32_e32 v186, v212, v186, vcc
	v_cmp_le_i32_e32 vcc, v243, v194
	s_nop 1
	v_cndmask_b32_e32 v187, v212, v187, vcc

.LBB0_485:
	v_mul_f32_e32 v229, 0xbe0293ee, v228
	v_fmamk_f32 v164, v164, 0x3e0293ee, v229
	v_exp_f32_e32 v231, v164
	v_fmamk_f32 v164, v165, 0x3e0293ee, v229
	v_exp_f32_e32 v233, v164
	v_fmamk_f32 v164, v166, 0x3e0293ee, v229
	v_exp_f32_e32 v235, v164
	v_fmamk_f32 v164, v167, 0x3e0293ee, v229
	v_exp_f32_e32 v237, v164
	v_fmamk_f32 v164, v180, 0x3e0293ee, v229
	v_exp_f32_e32 v239, v164
	v_fmamk_f32 v164, v181, 0x3e0293ee, v229
	v_exp_f32_e32 v181, v164
	v_fmamk_f32 v164, v182, 0x3e0293ee, v229
	v_exp_f32_e32 v241, v164
	v_fmamk_f32 v164, v183, 0x3e0293ee, v229
	v_exp_f32_e32 v183, v164
	v_fmamk_f32 v164, v176, 0x3e0293ee, v229
	v_exp_f32_e32 v243, v164
	v_fmamk_f32 v164, v177, 0x3e0293ee, v229
	v_mul_f32_e32 v166, 0xbe0293ee, v227
	v_exp_f32_e32 v177, v164
	v_fmamk_f32 v164, v178, 0x3e0293ee, v229
	v_fmamk_f32 v160, v160, 0x3e0293ee, v166
	v_exp_f32_e32 v245, v164
	v_fmamk_f32 v164, v179, 0x3e0293ee, v229
	v_exp_f32_e32 v230, v160
	v_fmamk_f32 v160, v161, 0x3e0293ee, v166
	v_exp_f32_e32 v179, v164
	v_fmamk_f32 v164, v188, 0x3e0293ee, v229
	v_exp_f32_e32 v232, v160
	v_fmamk_f32 v160, v162, 0x3e0293ee, v166
	v_exp_f32_e32 v247, v164
	v_fmamk_f32 v164, v189, 0x3e0293ee, v229
	v_exp_f32_e32 v234, v160
	v_fmamk_f32 v160, v163, 0x3e0293ee, v166
	v_exp_f32_e32 v189, v164
	v_fmamk_f32 v164, v190, 0x3e0293ee, v229
	v_exp_f32_e32 v236, v160
	v_fmamk_f32 v160, v172, 0x3e0293ee, v166
	v_exp_f32_e32 v249, v164
	v_exp_f32_e32 v238, v160
	v_fmamk_f32 v160, v173, 0x3e0293ee, v166
	v_pk_add_f32 v[164:165], v[230:231], 0 op_sel_hi:[1,0]
	v_exp_f32_e32 v180, v160
	v_pk_add_f32 v[164:165], v[232:233], v[164:165]
	v_fmamk_f32 v163, v174, 0x3e0293ee, v166
	v_pk_add_f32 v[164:165], v[234:235], v[164:165]
	v_exp_f32_e32 v240, v163
	v_fmamk_f32 v163, v175, 0x3e0293ee, v166
	v_pk_add_f32 v[164:165], v[236:237], v[164:165]
	v_exp_f32_e32 v182, v163
	v_fmamk_f32 v163, v168, 0x3e0293ee, v166
	v_pk_add_f32 v[164:165], v[238:239], v[164:165]
	v_exp_f32_e32 v242, v163
	v_fmamk_f32 v163, v169, 0x3e0293ee, v166
	v_pk_add_f32 v[164:165], v[180:181], v[164:165]
	v_exp_f32_e32 v176, v163
	v_fmamk_f32 v163, v170, 0x3e0293ee, v166
	v_exp_f32_e32 v244, v163
	v_fmamk_f32 v163, v171, 0x3e0293ee, v166
	v_pk_add_f32 v[164:165], v[240:241], v[164:165]
	v_exp_f32_e32 v178, v163
	v_fmamk_f32 v163, v184, 0x3e0293ee, v166
	v_pk_add_f32 v[164:165], v[182:183], v[164:165]
	v_exp_f32_e32 v246, v163
	v_fmamk_f32 v163, v185, 0x3e0293ee, v166
	v_pk_add_f32 v[164:165], v[242:243], v[164:165]
	v_exp_f32_e32 v188, v163
	v_fmamk_f32 v163, v186, 0x3e0293ee, v166
	v_pk_add_f32 v[164:165], v[176:177], v[164:165]
	v_fmac_f32_e32 v229, 0x3e0293ee, v191
	v_exp_f32_e32 v248, v163
	v_fmac_f32_e32 v166, 0x3e0293ee, v187
	v_pk_add_f32 v[164:165], v[244:245], v[164:165]
	v_exp_f32_e32 v191, v229
	v_exp_f32_e32 v190, v166
	v_pk_add_f32 v[164:165], v[178:179], v[164:165]
	v_cvt_pk_bf16_f32 v160, v231, v233
	v_cvt_pk_bf16_f32 v161, v235, v237
	v_cvt_pk_bf16_f32 v162, v239, v181
	v_cvt_pk_bf16_f32 v163, v241, v183
	s_nop 0
	v_pk_add_f32 v[164:165], v[246:247], v[164:165]
	s_nop 0
	v_pk_add_f32 v[164:165], v[188:189], v[164:165]
	s_nop 0
	v_pk_add_f32 v[164:165], v[248:249], v[164:165]
	s_nop 0
	v_pk_add_f32 v[168:169], v[190:191], v[164:165]
	v_cvt_pk_bf16_f32 v164, v243, v177
	v_cvt_pk_bf16_f32 v165, v245, v179
	v_cvt_pk_bf16_f32 v166, v247, v189
	v_cvt_pk_bf16_f32 v167, v249, v191
	s_nop 0
	v_pk_add_f32 v[196:197], v[196:197], v[168:169]
	v_cvt_pk_bf16_f32 v168, v230, v232
	v_cvt_pk_bf16_f32 v169, v234, v236
	v_cvt_pk_bf16_f32 v170, v238, v180
	v_cvt_pk_bf16_f32 v171, v240, v182
	v_cvt_pk_bf16_f32 v172, v242, v176
	v_cvt_pk_bf16_f32 v173, v244, v178
	v_cvt_pk_bf16_f32 v174, v246, v188
	v_cvt_pk_bf16_f32 v175, v248, v190
	s_branch .LBB0_486
.Lx_inact:
	s_and_b64 vcc, exec, s[0:1]
	s_cbranch_vccnz .LBB0_486
	s_barrier
	s_cmp_ge_u32 s41, s69
	s_cbranch_scc1 .Lx_nodma_i
	s_lshl_b32 s4, s76, 15
	s_add_i32 s4, s4, 0x8000
	s_cmp_lg_u32 s76, 2
	s_cselect_b32 s4, s4, 0
	s_and_b32 s5, s36, 0x4000
	s_add_i32 s5, s30, s5
	v_lshl_add_u64 v[236:237], v[200:201], 0, s[36:37]
	v_lshl_add_u64 v[236:237], v[236:237], 0, s[20:21]
	s_mov_b32 m0, s5
	s_add_i32 s4, s30, s4
	global_load_lds_dwordx4 v[236:237], off
	v_lshl_add_u64 v[236:237], v[202:203], 0, s[36:37]
	v_lshl_add_u64 v[236:237], v[236:237], 0, s[20:21]
	s_add_i32 m0, s5, 0x2000
	s_nop 0
	global_load_lds_dwordx4 v[236:237], off
	v_lshl_add_u64 v[236:237], v[204:205], 0, s[36:37]
	v_lshl_add_u64 v[238:239], v[236:237], 0, s[20:21]
	s_add_i32 m0, s4, 0x8000
	v_lshl_add_u64 v[236:237], v[236:237], 0, s[22:23]
	global_load_lds_dwordx4 v[238:239], off
	v_lshl_add_u64 v[238:239], v[206:207], 0, s[36:37]
	v_lshl_add_u64 v[240:241], v[238:239], 0, s[20:21]
	s_add_i32 m0, s4, 0xa000
	s_nop 0
	global_load_lds_dwordx4 v[240:241], off
	s_add_i32 m0, s4, 0xc000
	s_nop 0
	global_load_lds_dwordx4 v[236:237], off
	s_add_i32 m0, s4, 0xe000
	v_lshl_add_u64 v[236:237], v[238:239], 0, s[22:23]
	global_load_lds_dwordx4 v[236:237], off
.Lx_nodma_i:
.LBB0_486:
	s_and_b64 vcc, exec, s[0:1]
	s_cbranch_vccz .Lx_late_hash
	s_barrier
	s_cmp_ge_u32 s41, s69
	s_cbranch_scc1 .Lx_nodma_e
	s_lshl_b32 s4, s76, 15
	s_add_i32 s4, s4, 0x8000
	s_cmp_lg_u32 s76, 2
	s_cselect_b32 s4, s4, 0
	s_and_b32 s5, s36, 0x4000
	s_add_i32 s5, s30, s5
	v_lshl_add_u64 v[236:237], v[200:201], 0, s[36:37]
	v_lshl_add_u64 v[236:237], v[236:237], 0, s[20:21]
	s_mov_b32 m0, s5
	s_add_i32 s4, s30, s4
	global_load_lds_dwordx4 v[236:237], off
	v_lshl_add_u64 v[236:237], v[202:203], 0, s[36:37]
	v_lshl_add_u64 v[236:237], v[236:237], 0, s[20:21]
	s_add_i32 m0, s5, 0x2000
	s_nop 0
	global_load_lds_dwordx4 v[236:237], off
	v_lshl_add_u64 v[236:237], v[204:205], 0, s[36:37]
	v_lshl_add_u64 v[238:239], v[236:237], 0, s[20:21]
	s_add_i32 m0, s4, 0x8000
	v_lshl_add_u64 v[236:237], v[236:237], 0, s[22:23]
	global_load_lds_dwordx4 v[238:239], off
	v_lshl_add_u64 v[238:239], v[206:207], 0, s[36:37]
	v_lshl_add_u64 v[240:241], v[238:239], 0, s[20:21]
	s_add_i32 m0, s4, 0xa000
	s_nop 0
	global_load_lds_dwordx4 v[240:241], off
	s_add_i32 m0, s4, 0xc000
	s_nop 0
	global_load_lds_dwordx4 v[236:237], off
	s_add_i32 m0, s4, 0xe000
	v_lshl_add_u64 v[236:237], v[238:239], 0, s[22:23]
	global_load_lds_dwordx4 v[236:237], off
.Lx_nodma_e:
	s_branch .LBB0_489
.Lx_late_hash:
	s_cmp_lt_u32 s41, s69
	s_cbranch_scc1 .Lx_w6_b
	s_waitcnt vmcnt(0)
	s_branch .Lx_wd_b
